# PB attention: for query blocks at the sequence ends, key blocks entirely outside the sequence are skipped and interior blocks drop the per-element mask (edge CUs were the PB critical path)
# speedup vs baseline: 1.0073x; 1.0024x over previous
; __device__ __forceinline__ void attn_unit(LAS unsigned char* lds, const bf16* PROJ, bf16* DA, const float* sinkl, int unit, int tid, int wid, int lane) {
;     ...
;         const int a0 = 64 * (wid & 1) + 32 * sb, a = a0 + r32;
.LBB0_380:
	s_or_b32 s24, s23, s80
	s_or_b32 s89, s23, s80
	v_or_b32_e32 v4, s24, v85
	v_or_b32_e32 v2, s12, v4
	v_or_b32_e32 v90, s6, v2
	v_mad_u64_u32 v[2:3], s[24:25], v90, s82, v[86:87]
	v_mad_i32_i24 v3, s7, v201, v3
	s_cmp_eq_u32 s23, 0
	s_cbranch_scc1 .Lq_skip1
	global_load_dwordx4 v[68:71], v[2:3], off offset:1024
	global_load_dwordx4 v[72:75], v[2:3], off offset:1056
	global_load_dwordx4 v[76:79], v[2:3], off offset:1088
	global_load_dwordx4 v[80:83], v[2:3], off offset:1120

; __device__ __forceinline__ void attn_unit(LAS unsigned char* lds, const bf16* PROJ, bf16* DA, const float* sinkl, int unit, int tid, int wid, int lane) {
;     ...
;             if ((i == 0) || (i == 8) || edge_n) {
.Lalibi_done:
	s_cmp_eq_u32 s78, 0
	s_cbranch_scc1 .Ledge_lo
	s_cmp_eq_u32 s78, 31
	s_cbranch_scc1 .Ledge_hi
	s_and_b32 s25, s24, 7
	s_cmp_eq_u32 s25, 0
	s_cbranch_scc1 .LBB0_391
	s_cmp_gt_i32 s78, 30
	s_mov_b64 s[38:39], -1
	s_cbranch_scc1 .LBB0_385
	s_cmp_eq_u32 s78, 0
	s_cselect_b64 s[38:39], -1, 0

; #define ATT_QK(dst, cblk) do { _Pragma("unroll") for (int r = 0; r < 16; ++r) dst[r] = 0.f; \
;             _Pragma("unroll") for (int ks = 0; ks < 4; ++ks) { const bf16x8 kf = *(const LAS bf16x8*)(Ks + ((cblk) + r32) * KS_PITCH + ks * 16 + hi * 8); \
;                 dst = __builtin_amdgcn_mfma_f32_32x32x16_bf16(kf, qf[ks], dst, 0, 0, 0); } } while (0)
; __device__ __forceinline__ void attn_unit(LAS unsigned char* lds, const bf16* PROJ, bf16* DA, const float* sinkl, int unit, int tid, int wid, int lane) {
;     ...
;         for (int i = 0; i < 9; ++i) {
;             const int c0 = a0 + 32 * i;
;             f32x16 p = pn;
;             if (i < 8) ATT_QK(pn, c0 + 32);
.Lblk_tail:
	s_cmpk_eq_i32 s23, 0xfee0
	v_add_u32_e32 v92, 0x1200, v92
	s_cbranch_scc1 .LBB0_379
	s_cmp_gt_i32 s23, 0xffffff80
	s_cbranch_scc1 .Lqa_pos
	s_cmp_eq_u32 s23, 0xffffff80
	s_cbranch_scc1 .Lqa_zero
	v_mfma_f32_32x32x16_bf16 v[50:65], v[174:177], v[68:71], v[220:235]
	s_branch .Lqa_done

; __device__ __forceinline__ void attn_unit(LAS unsigned char* lds, const bf16* PROJ, bf16* DA, const float* sinkl, int unit, int tid, int wid, int lane) {
;     ...
;             const float kmin = fmaxf(fb - 128.0f, (float)(-sb0)), kmax = fminf(fb + 128.0f, (float)(SEQ - 1 - sb0));
;             const float kmid = 0.5f * (kmin + kmax), khw = 0.5f * (kmax - kmin);
;             float mx = NEG;
; #pragma unroll
;             for (int r = 0; r < 16; ++r) { const float kr = (float)((r & 3) + 8 * (r >> 2)); p[r] = p[r] - slope2 * fabsf(fb - kr); }
;             if ((i == 0) || (i == 8) || edge_n) {
; #pragma unroll
;                 for (int r = 0; r < 16; ++r) { const float kr = (float)((r & 3) + 8 * (r >> 2)); p[r] = (fabsf(kr - kmid) <= khw) ? p[r] : NEG; }
.Ledge_lo:
	s_sub_i32 s88, s89, s23
	s_cmp_le_i32 s88, 0x60
	s_cbranch_scc1 .Lblk_skip
	s_branch .Ledge_valid
.Ledge_hi:
	s_sub_i32 s88, s89, s23
	s_cmp_ge_i32 s88, 0x100
	s_cbranch_scc1 .Lblk_skip
.Ledge_valid:
	s_and_b32 s25, s24, 7
	s_cmp_eq_u32 s25, 0
	s_cbranch_scc1 .LBB0_386
	s_branch .LBB0_387
.Lblk_skip:
	s_add_i32 s24, s24, 1
	s_sub_i32 s23, s23, 32
	v_add_u32_e32 v100, 64, v100
	v_add_u32_e32 v101, 64, v101
	s_waitcnt lgkmcnt(0)
	s_branch .Lblk_tail
